# attention loop v2: LDS write block and V fragment reads overlapped with QK MFMAs, SGPR address bases
# speedup vs baseline: 1.0110x; 1.0110x over previous
.LBB0_1038:
	s_or_b64 exec, exec, s[4:5]
	v_and_b32_e32 v0, 0x60, v26
	s_movk_i32 s4, 0x90
	v_lshlrev_b32_e32 v2, 3, v32
	v_mad_u32_u24 v207, v203, s4, 0
	v_mad_u64_u32 v[0:1], s[4:5], v28, s4, v[0:1]
	v_and_or_b32 v0, v2, 8, v0
	v_lshlrev_b32_e32 v1, 6, v203
	v_add_u32_e32 v208, 0, v0
	v_add3_u32 v204, v207, v1, v184
	v_add_u32_e32 v1, 0, v4
	v_add_u32_e32 v205, 0x9800, v208
	s_waitcnt vmcnt(3)
	ds_write_b128 v1, v[8:11] offset:13312
	s_waitcnt vmcnt(2)
	ds_write2_b64 v205, v[16:17], v[18:19] offset0:128 offset1:130
	s_waitcnt lgkmcnt(0)
	s_barrier
	ds_read_b128 v[0:3], v204
	ds_read_b128 v[4:7], v204 offset:32
	ds_read_b128 v[8:11], v204 offset:6656
	ds_read_b128 v[12:15], v204 offset:6688
	ds_read_b128 v[16:19], v204 offset:64
	ds_read_b128 v[28:31], v204 offset:96
	ds_read_b128 v[64:67], v204 offset:6720
	ds_read_b128 v[68:71], v204 offset:6752
	ds_read_b128 v[72:75], v204 offset:128
	ds_read_b128 v[76:79], v204 offset:160
	ds_read_b128 v[80:83], v204 offset:6784
	ds_read_b128 v[84:87], v204 offset:6816
	s_mov_b32 s91, 2
	s_lshl_b32 s87, s6, 2
	s_waitcnt lgkmcnt(11)
	v_mfma_f32_32x32x16_bf16 v[48:63], v[0:3], v[100:103], 0
	s_mov_b32 s79, 0
	s_waitcnt lgkmcnt(9)
	v_mfma_f32_32x32x16_bf16 v[32:47], v[8:11], v[100:103], 0
	v_mfma_f32_32x32x16_bf16 v[48:63], v[4:7], v[104:107], v[48:63]
	s_waitcnt lgkmcnt(8)
	v_mfma_f32_32x32x16_bf16 v[32:47], v[12:15], v[104:107], v[32:47]
	s_waitcnt lgkmcnt(7)
	v_mfma_f32_32x32x16_bf16 v[48:63], v[16:19], v[108:111], v[48:63]
	s_waitcnt lgkmcnt(5)
	v_mfma_f32_32x32x16_bf16 v[32:47], v[64:67], v[108:111], v[32:47]
	v_mfma_f32_32x32x16_bf16 v[48:63], v[28:31], v[112:115], v[48:63]
	s_waitcnt lgkmcnt(4)
	v_mfma_f32_32x32x16_bf16 v[32:47], v[68:71], v[112:115], v[32:47]
	s_waitcnt lgkmcnt(3)
	v_mfma_f32_32x32x16_bf16 v[48:63], v[72:75], v[116:119], v[48:63]
	s_waitcnt lgkmcnt(1)
	v_mfma_f32_32x32x16_bf16 v[32:47], v[80:83], v[116:119], v[32:47]
	v_mfma_f32_32x32x16_bf16 v[48:63], v[76:79], v[120:123], v[48:63]
	s_waitcnt lgkmcnt(0)
	v_mfma_f32_32x32x16_bf16 v[32:47], v[84:87], v[120:123], v[32:47]
	ds_read_b128 v[172:175], v204 offset:13312
	ds_read_b128 v[152:155], v204 offset:13344
	ds_read_b128 v[180:183], v204 offset:19968
	ds_read_b128 v[164:167], v204 offset:20000
	ds_read_b128 v[156:159], v204 offset:13376
	ds_read_b128 v[140:143], v204 offset:13408
	ds_read_b128 v[176:179], v204 offset:20032
	ds_read_b128 v[160:163], v204 offset:20064
	ds_read_b128 v[148:151], v204 offset:13440
	ds_read_b128 v[136:139], v204 offset:13472
	ds_read_b128 v[168:171], v204 offset:20096
	ds_read_b128 v[144:147], v204 offset:20128
	s_add_u32 s4, s60, 0x100
	v_lshl_add_u64 v[0:1], s[60:61], 0, v[24:25]
	v_mov_b32_e32 v27, v97
	s_addc_u32 s5, 0, 0
	v_lshl_add_u64 v[190:191], v[0:1], 0, v[26:27]
	v_lshl_add_u64 v[0:1], s[4:5], 0, v[24:25]
	v_mov_b32_e32 v199, 0
	v_lshl_add_u64 v[188:189], s[96:97], 0, v[20:21]
	v_lshl_add_u64 v[186:187], s[96:97], 0, v[22:23]
	v_lshl_add_u64 v[98:99], v[0:1], 0, v[26:27]
	s_add_u32 s98, s94, 0x12209000
	s_addc_u32 s99, s95, 0
	s_add_u32 s100, s94, 0x11200000
	s_addc_u32 s101, s95, 0

	s_movk_i32 s93, 0xbf
	v_mov_b32_e32 v0, 0
	v_mov_b32_e32 v1, v199
	v_mov_b32_e32 v2, v199
	v_mov_b32_e32 v3, v199
	v_mov_b32_e32 v4, v199
	v_mov_b32_e32 v5, v199
	v_mov_b32_e32 v6, v199
	v_mov_b32_e32 v7, v199
	v_mov_b32_e32 v8, v199
	v_mov_b32_e32 v9, v199
	v_mov_b32_e32 v10, v199
	v_mov_b32_e32 v11, v199
	v_mov_b32_e32 v12, v199
	v_mov_b32_e32 v13, v199
	v_mov_b32_e32 v14, v199
	v_mov_b32_e32 v15, v199
	v_mov_b32_e32 v16, 0
	v_mov_b32_e32 v17, v199
	v_mov_b32_e32 v18, v199
	v_mov_b32_e32 v19, v199
	v_mov_b32_e32 v20, v199
	v_mov_b32_e32 v21, v199
	v_mov_b32_e32 v22, v199
	v_mov_b32_e32 v23, v199
	v_mov_b32_e32 v24, v199
	v_mov_b32_e32 v25, v199
	v_mov_b32_e32 v26, v199
	v_mov_b32_e32 v27, v199
	v_mov_b32_e32 v28, v199
	v_mov_b32_e32 v29, v199
	v_mov_b32_e32 v30, v199
	v_mov_b32_e32 v31, v199
.LBB0_1039:
	s_waitcnt lgkmcnt(11)
	v_mfma_f32_32x32x16_bf16 v[64:79], v[172:175], v[100:103], 0
	v_exp_f32_e32 v48, v48
	v_exp_f32_e32 v49, v49
	v_exp_f32_e32 v50, v50
	v_add_f32_e32 v195, v48, v49
	v_exp_f32_e32 v51, v51
	s_waitcnt lgkmcnt(9)
	v_mfma_f32_32x32x16_bf16 v[80:95], v[180:183], v[100:103], 0
	v_add_f32_e32 v195, v50, v195
	v_exp_f32_e32 v52, v52
	v_add_f32_e32 v195, v51, v195
	v_exp_f32_e32 v53, v53
	v_add_f32_e32 v195, v52, v195
	v_exp_f32_e32 v54, v54
	v_add_f32_e32 v195, v53, v195
	v_mfma_f32_32x32x16_bf16 v[64:79], v[152:155], v[104:107], v[64:79]
	v_exp_f32_e32 v55, v55
	v_add_f32_e32 v195, v54, v195
	v_exp_f32_e32 v56, v56
	v_add_f32_e32 v195, v55, v195
	v_exp_f32_e32 v57, v57
	v_add_f32_e32 v195, v56, v195
	s_waitcnt lgkmcnt(8)
	v_mfma_f32_32x32x16_bf16 v[80:95], v[164:167], v[104:107], v[80:95]
	v_exp_f32_e32 v58, v58
	v_add_f32_e32 v195, v57, v195
	v_exp_f32_e32 v59, v59
	v_add_f32_e32 v195, v58, v195
	v_exp_f32_e32 v60, v60
	v_add_f32_e32 v195, v59, v195
	s_waitcnt lgkmcnt(7)
	v_mfma_f32_32x32x16_bf16 v[64:79], v[156:159], v[108:111], v[64:79]
	v_exp_f32_e32 v61, v61
	v_add_f32_e32 v195, v60, v195
	v_exp_f32_e32 v62, v62
	v_add_f32_e32 v195, v61, v195
	v_exp_f32_e32 v63, v63
	v_add_f32_e32 v195, v62, v195
	v_add_f32_e32 v195, v63, v195
	s_mul_i32 s6, s91, 0x3400
	s_add_i32 s7, s6, 0

	v_add_u32_e32 v253, s7, v96
	s_waitcnt vmcnt(1)
	ds_write_b128 v253, v[128:131]
	s_and_saveexec_b64 s[4:5], s[2:3]
	v_add_u32_e32 v253, s7, v185
	ds_write_b128 v253, v[124:127]
	s_or_b64 exec, exec, s[4:5]
	v_lshl_add_u64 v[200:201], s[100:101], 0, v[190:191]

	v_add_u32_e32 v206, 0xc000, v208
	v_lshl_add_u64 v[128:129], s[98:99], 0, v[188:189]
	s_nop 0
	global_load_dwordx4 v[128:131], v[128:129], off
	s_waitcnt vmcnt(1)
	ds_write2_b64 v206, v[132:133], v[134:135] offset1:2

	s_and_saveexec_b64 s[4:5], s[2:3]
	s_cbranch_execz .LatA_h0
	v_lshl_add_u64 v[124:125], s[98:99], 0, v[186:187]
	s_nop 0
	global_load_dwordx4 v[124:127], v[124:125], off
.LatA_h0:
	s_or_b64 exec, exec, s[4:5]
	global_load_dwordx4 v[132:135], v[200:201], off offset:256

	s_waitcnt lgkmcnt(7)
	v_mfma_f32_32x32x16_bf16 v[80:95], v[176:179], v[108:111], v[80:95]
	v_exp_f32_e32 v32, v32
	v_exp_f32_e32 v33, v33
	v_exp_f32_e32 v34, v34
	v_add_f32_e32 v251, v32, v33
	v_cvt_pk_bf16_f32 v48, v48, v49
	v_exp_f32_e32 v35, v35
	v_mfma_f32_32x32x16_bf16 v[64:79], v[140:143], v[112:115], v[64:79]
	v_add_f32_e32 v251, v34, v251
	v_exp_f32_e32 v36, v36
	v_add_f32_e32 v251, v35, v251
	v_cvt_pk_bf16_f32 v49, v50, v51
	v_exp_f32_e32 v37, v37
	v_add_f32_e32 v251, v36, v251
	s_waitcnt lgkmcnt(6)
	v_mfma_f32_32x32x16_bf16 v[80:95], v[160:163], v[112:115], v[80:95]
	v_exp_f32_e32 v38, v38
	v_add_f32_e32 v251, v37, v251
	v_cvt_pk_bf16_f32 v50, v52, v53
	v_exp_f32_e32 v39, v39
	v_add_f32_e32 v251, v38, v251
	v_exp_f32_e32 v40, v40
	v_add_f32_e32 v251, v39, v251
	s_waitcnt lgkmcnt(5)
	v_mfma_f32_32x32x16_bf16 v[64:79], v[148:151], v[116:119], v[64:79]
	v_cvt_pk_bf16_f32 v51, v54, v55
	v_exp_f32_e32 v41, v41
	v_add_f32_e32 v251, v40, v251
	v_exp_f32_e32 v42, v42
	v_add_f32_e32 v251, v41, v251
	v_cvt_pk_bf16_f32 v52, v56, v57
	v_exp_f32_e32 v43, v43
	v_add_u32_e32 v198, v207, v184
	ds_read_b128 v[210:213], v198 offset:44544
	ds_read_b128 v[214:217], v198 offset:39936
	ds_read_b128 v[218:221], v198 offset:39968
	ds_read_b128 v[222:225], v198 offset:44576
	ds_read_b128 v[226:229], v198 offset:40000
	ds_read_b128 v[230:233], v198 offset:44608
	ds_read_b128 v[234:237], v198 offset:40032
	ds_read_b128 v[238:241], v198 offset:44640
	s_waitcnt lgkmcnt(11)
	v_mfma_f32_32x32x16_bf16 v[80:95], v[168:171], v[116:119], v[80:95]
	v_add_f32_e32 v251, v42, v251
	v_exp_f32_e32 v44, v44
	v_add_f32_e32 v251, v43, v251
	v_cvt_pk_bf16_f32 v53, v58, v59
	v_exp_f32_e32 v45, v45
	v_add_f32_e32 v251, v44, v251
	v_mfma_f32_32x32x16_bf16 v[64:79], v[136:139], v[120:123], v[64:79]
	v_exp_f32_e32 v46, v46
	v_add_f32_e32 v251, v45, v251
	v_cvt_pk_bf16_f32 v54, v60, v61
	v_exp_f32_e32 v47, v47
	v_add_f32_e32 v251, v46, v251
	v_add_f32_e32 v251, v47, v251
	v_cvt_pk_bf16_f32 v55, v62, v63
	v_cvt_pk_bf16_f32 v32, v32, v33
	s_waitcnt lgkmcnt(10)
	v_mfma_f32_32x32x16_bf16 v[80:95], v[144:147], v[120:123], v[80:95]
	v_cvt_pk_bf16_f32 v33, v34, v35
	v_cvt_pk_bf16_f32 v34, v36, v37
	v_cvt_pk_bf16_f32 v35, v38, v39
	v_cvt_pk_bf16_f32 v36, v40, v41
	v_cvt_pk_bf16_f32 v37, v42, v43
	v_cvt_pk_bf16_f32 v38, v44, v45
	v_cvt_pk_bf16_f32 v39, v46, v47
	v_add_f32_e32 v195, v195, v251
	v_add_f32_e32 v199, v199, v195
	s_waitcnt lgkmcnt(0)
	s_barrier

	v_add_u32_e32 v197, s6, v204
	s_setprio 1
	v_mfma_f32_32x32x16_bf16 v[0:15], v[48:51], v[210:213], v[0:15]
	ds_read_b128 v[172:175], v197
	ds_read_b128 v[152:155], v197 offset:32
	v_mfma_f32_32x32x16_bf16 v[0:15], v[52:55], v[222:225], v[0:15]
	ds_read_b128 v[180:183], v197 offset:6656
	ds_read_b128 v[164:167], v197 offset:6688
	v_mfma_f32_32x32x16_bf16 v[0:15], v[32:35], v[230:233], v[0:15]
	ds_read_b128 v[156:159], v197 offset:64
	ds_read_b128 v[140:143], v197 offset:96
	v_mfma_f32_32x32x16_bf16 v[0:15], v[36:39], v[238:241], v[0:15]
	s_setprio 0
	ds_read_b128 v[176:179], v197 offset:6720
	ds_read_b128 v[160:163], v197 offset:6752
	v_mfma_f32_32x32x16_bf16 v[16:31], v[48:51], v[214:217], v[16:31]
	ds_read_b128 v[148:151], v197 offset:128
	ds_read_b128 v[136:139], v197 offset:160
	v_mfma_f32_32x32x16_bf16 v[16:31], v[52:55], v[218:221], v[16:31]
	ds_read_b128 v[168:171], v197 offset:6784
	ds_read_b128 v[144:147], v197 offset:6816
	v_mfma_f32_32x32x16_bf16 v[16:31], v[32:35], v[226:229], v[16:31]
	v_mfma_f32_32x32x16_bf16 v[16:31], v[36:39], v[234:237], v[16:31]
	s_waitcnt lgkmcnt(11)
	v_mfma_f32_32x32x16_bf16 v[48:63], v[172:175], v[100:103], 0
	v_exp_f32_e32 v64, v64
	v_exp_f32_e32 v65, v65
	v_exp_f32_e32 v66, v66
	v_add_f32_e32 v195, v64, v65
	v_exp_f32_e32 v67, v67
	s_waitcnt lgkmcnt(9)
	v_mfma_f32_32x32x16_bf16 v[32:47], v[180:183], v[100:103], 0
	v_add_f32_e32 v195, v66, v195
	v_exp_f32_e32 v68, v68
	v_add_f32_e32 v195, v67, v195
	v_exp_f32_e32 v69, v69
	v_add_f32_e32 v195, v68, v195
	v_exp_f32_e32 v70, v70
	v_add_f32_e32 v195, v69, v195
	v_mfma_f32_32x32x16_bf16 v[48:63], v[152:155], v[104:107], v[48:63]
	v_exp_f32_e32 v71, v71
	v_add_f32_e32 v195, v70, v195
	v_exp_f32_e32 v72, v72
	v_add_f32_e32 v195, v71, v195
	v_exp_f32_e32 v73, v73
	v_add_f32_e32 v195, v72, v195
	s_waitcnt lgkmcnt(8)
	v_mfma_f32_32x32x16_bf16 v[32:47], v[164:167], v[104:107], v[32:47]
	v_exp_f32_e32 v74, v74
	v_add_f32_e32 v195, v73, v195
	v_exp_f32_e32 v75, v75
	v_add_f32_e32 v195, v74, v195
	v_exp_f32_e32 v76, v76
	v_add_f32_e32 v195, v75, v195
	s_waitcnt lgkmcnt(7)
	v_mfma_f32_32x32x16_bf16 v[48:63], v[156:159], v[108:111], v[48:63]
	v_exp_f32_e32 v77, v77
	v_add_f32_e32 v195, v76, v195
	v_exp_f32_e32 v78, v78
	v_add_f32_e32 v195, v77, v195
	v_exp_f32_e32 v79, v79
	v_add_f32_e32 v195, v78, v195
	v_add_f32_e32 v195, v79, v195
	s_add_i32 s4, s91, 1
	s_cmp_lg_u32 s91, 2
	s_cselect_b32 s74, s4, 0
	s_mul_i32 s6, s74, 0x3400
	s_add_i32 s7, s6, 0
	s_add_u32 s98, s98, 0x3000
	s_addc_u32 s99, s99, 0

	v_add_u32_e32 v253, s7, v96
	s_waitcnt vmcnt(1)
	ds_write_b128 v253, v[128:131]
	s_and_saveexec_b64 s[4:5], s[2:3]
	v_add_u32_e32 v253, s7, v185
	ds_write_b128 v253, v[124:127]
	s_or_b64 exec, exec, s[4:5]
	v_lshl_add_u64 v[200:201], s[100:101], 0, v[190:191]

	s_waitcnt vmcnt(0)
	ds_write2_b64 v205, v[132:133], v[134:135] offset0:128 offset1:130
	v_lshl_add_u64 v[128:129], s[98:99], 0, v[188:189]
	s_nop 0
	global_load_dwordx4 v[128:131], v[128:129], off

	s_and_saveexec_b64 s[4:5], s[2:3]
	s_cbranch_execz .LatA_h1
	v_lshl_add_u64 v[124:125], s[98:99], 0, v[186:187]
	s_nop 0
	global_load_dwordx4 v[124:127], v[124:125], off
.LatA_h1:
	s_or_b64 exec, exec, s[4:5]
	global_load_dwordx4 v[132:135], v[200:201], off offset:384

	s_sub_u32 s98, s98, 0x3000
	s_subb_u32 s99, s99, 0

	s_waitcnt lgkmcnt(7)
	v_mfma_f32_32x32x16_bf16 v[32:47], v[176:179], v[108:111], v[32:47]
	v_exp_f32_e32 v80, v80
	v_exp_f32_e32 v81, v81
	v_exp_f32_e32 v82, v82
	v_add_f32_e32 v251, v80, v81
	v_cvt_pk_bf16_f32 v64, v64, v65
	v_exp_f32_e32 v83, v83
	v_mfma_f32_32x32x16_bf16 v[48:63], v[140:143], v[112:115], v[48:63]
	v_add_f32_e32 v251, v82, v251
	v_exp_f32_e32 v84, v84
	v_add_f32_e32 v251, v83, v251
	v_cvt_pk_bf16_f32 v65, v66, v67
	v_exp_f32_e32 v85, v85
	v_add_f32_e32 v251, v84, v251
	s_waitcnt lgkmcnt(6)
	v_mfma_f32_32x32x16_bf16 v[32:47], v[160:163], v[112:115], v[32:47]
	v_exp_f32_e32 v86, v86
	v_add_f32_e32 v251, v85, v251
	v_cvt_pk_bf16_f32 v66, v68, v69
	v_exp_f32_e32 v87, v87
	v_add_f32_e32 v251, v86, v251
	v_exp_f32_e32 v88, v88
	v_add_f32_e32 v251, v87, v251
	s_waitcnt lgkmcnt(5)
	v_mfma_f32_32x32x16_bf16 v[48:63], v[148:151], v[116:119], v[48:63]
	v_cvt_pk_bf16_f32 v67, v70, v71
	v_exp_f32_e32 v89, v89
	v_add_f32_e32 v251, v88, v251
	v_exp_f32_e32 v90, v90
	v_add_f32_e32 v251, v89, v251
	v_cvt_pk_bf16_f32 v68, v72, v73
	v_exp_f32_e32 v91, v91
	v_add_u32_e32 v198, v207, v184
	ds_read_b128 v[210:213], v198 offset:53760
	ds_read_b128 v[214:217], v198 offset:49152
	ds_read_b128 v[218:221], v198 offset:49184
	ds_read_b128 v[222:225], v198 offset:53792
	ds_read_b128 v[226:229], v198 offset:49216
	ds_read_b128 v[230:233], v198 offset:53824
	ds_read_b128 v[234:237], v198 offset:49248
	ds_read_b128 v[238:241], v198 offset:53856
	s_waitcnt lgkmcnt(11)
	v_mfma_f32_32x32x16_bf16 v[32:47], v[168:171], v[116:119], v[32:47]
	v_add_f32_e32 v251, v90, v251
	v_exp_f32_e32 v92, v92
	v_add_f32_e32 v251, v91, v251
	v_cvt_pk_bf16_f32 v69, v74, v75
	v_exp_f32_e32 v93, v93
	v_add_f32_e32 v251, v92, v251
	v_mfma_f32_32x32x16_bf16 v[48:63], v[136:139], v[120:123], v[48:63]
	v_exp_f32_e32 v94, v94
	v_add_f32_e32 v251, v93, v251
	v_cvt_pk_bf16_f32 v70, v76, v77
	v_exp_f32_e32 v95, v95
	v_add_f32_e32 v251, v94, v251
	v_add_f32_e32 v251, v95, v251
	v_cvt_pk_bf16_f32 v71, v78, v79
	v_cvt_pk_bf16_f32 v80, v80, v81
	s_waitcnt lgkmcnt(10)
	v_mfma_f32_32x32x16_bf16 v[32:47], v[144:147], v[120:123], v[32:47]
	v_cvt_pk_bf16_f32 v81, v82, v83
	v_cvt_pk_bf16_f32 v82, v84, v85
	v_cvt_pk_bf16_f32 v83, v86, v87
	v_cvt_pk_bf16_f32 v84, v88, v89
	v_cvt_pk_bf16_f32 v85, v90, v91
	v_cvt_pk_bf16_f32 v86, v92, v93
	v_cvt_pk_bf16_f32 v87, v94, v95
	v_add_f32_e32 v195, v195, v251
	v_add_f32_e32 v199, v199, v195
	s_add_i32 s92, s79, 2
	s_waitcnt lgkmcnt(0)
	s_barrier

	v_add_u32_e32 v197, s6, v204
	s_setprio 1
	v_mfma_f32_32x32x16_bf16 v[0:15], v[64:67], v[210:213], v[0:15]
	ds_read_b128 v[172:175], v197
	ds_read_b128 v[152:155], v197 offset:32
	v_mfma_f32_32x32x16_bf16 v[0:15], v[68:71], v[222:225], v[0:15]
	ds_read_b128 v[180:183], v197 offset:6656
	ds_read_b128 v[164:167], v197 offset:6688
	v_mfma_f32_32x32x16_bf16 v[0:15], v[80:83], v[230:233], v[0:15]
	ds_read_b128 v[156:159], v197 offset:64
	ds_read_b128 v[140:143], v197 offset:96
	v_mfma_f32_32x32x16_bf16 v[0:15], v[84:87], v[238:241], v[0:15]
	s_setprio 0
	ds_read_b128 v[176:179], v197 offset:6720
	ds_read_b128 v[160:163], v197 offset:6752
	v_mfma_f32_32x32x16_bf16 v[16:31], v[64:67], v[214:217], v[16:31]
	ds_read_b128 v[148:151], v197 offset:128
	ds_read_b128 v[136:139], v197 offset:160
	v_mfma_f32_32x32x16_bf16 v[16:31], v[68:71], v[218:221], v[16:31]
	ds_read_b128 v[168:171], v197 offset:6784
	ds_read_b128 v[144:147], v197 offset:6816
	v_mfma_f32_32x32x16_bf16 v[16:31], v[80:83], v[226:229], v[16:31]
	v_mfma_f32_32x32x16_bf16 v[16:31], v[84:87], v[234:237], v[16:31]
	s_add_i32 s4, s74, 1
	s_cmp_lg_u32 s74, 2
	s_cselect_b32 s91, s4, 0
	s_add_i32 s4, s93, 0x80
	v_lshl_add_u64 v[188:189], v[188:189], 0, s[82:83]
	v_lshl_add_u64 v[186:187], v[186:187], 0, s[82:83]
	v_lshl_add_u64 v[190:191], v[190:191], 0, s[66:67]
	s_cmp_ge_u32 s92, s87
	v_lshl_add_u64 v[192:193], v[98:99], 0, s[66:67]
	s_cbranch_scc1 .LBB0_1049
	v_mov_b64_e32 v[98:99], v[192:193]
	s_mov_b32 s93, s4
	s_mov_b32 s79, s92
	s_branch .LBB0_1039


.LBB0_1103:
	s_or_b64 exec, exec, s[4:5]
	v_and_b32_e32 v2, 0x60, v190
	s_movk_i32 s4, 0x90
	v_lshlrev_b32_e32 v1, 3, v24
	v_mad_u32_u24 v208, v207, s4, 0
	v_mad_u64_u32 v[2:3], s[4:5], v20, s4, v[2:3]
	v_and_or_b32 v1, v1, 8, v2
	v_lshlrev_b32_e32 v2, 6, v207
	v_add_u32_e32 v210, 0, v1
	v_add3_u32 v209, v208, v2, v184
	v_add_u32_e32 v0, 0, v0
	v_add_u32_e32 v211, 0x9800, v210
	s_waitcnt vmcnt(3)
	ds_write_b128 v0, v[4:7] offset:13312
	s_waitcnt vmcnt(2)
	ds_write2_b64 v211, v[8:9], v[10:11] offset0:128 offset1:130
	s_waitcnt lgkmcnt(0)
	s_barrier
	ds_read_b128 v[0:3], v209
	ds_read_b128 v[4:7], v209 offset:32
	ds_read_b128 v[8:11], v209 offset:6656
	ds_read_b128 v[12:15], v209 offset:6688
	ds_read_b128 v[16:19], v209 offset:64
	ds_read_b128 v[20:23], v209 offset:96
	ds_read_b128 v[24:27], v209 offset:6720
	ds_read_b128 v[28:31], v209 offset:6752
	ds_read_b128 v[64:67], v209 offset:128
	ds_read_b128 v[68:71], v209 offset:160
	ds_read_b128 v[72:75], v209 offset:6784
	ds_read_b128 v[76:79], v209 offset:6816
	s_mov_b32 s90, 2
	s_lshl_b32 s69, s68, 2
	s_mov_b32 s40, 0
	s_cmp_eq_u32 s68, 0
	s_waitcnt lgkmcnt(11)
	v_mfma_f32_32x32x16_bf16 v[48:63], v[0:3], v[100:103], 0
	s_waitcnt lgkmcnt(9)
	v_mfma_f32_32x32x16_bf16 v[32:47], v[8:11], v[100:103], 0
	v_mfma_f32_32x32x16_bf16 v[48:63], v[4:7], v[104:107], v[48:63]
	s_waitcnt lgkmcnt(8)
	v_mfma_f32_32x32x16_bf16 v[32:47], v[12:15], v[104:107], v[32:47]
	s_waitcnt lgkmcnt(7)
	v_mfma_f32_32x32x16_bf16 v[48:63], v[16:19], v[108:111], v[48:63]
	s_waitcnt lgkmcnt(5)
	v_mfma_f32_32x32x16_bf16 v[32:47], v[24:27], v[108:111], v[32:47]
	v_mfma_f32_32x32x16_bf16 v[48:63], v[20:23], v[112:115], v[48:63]
	s_waitcnt lgkmcnt(4)
	v_mfma_f32_32x32x16_bf16 v[32:47], v[28:31], v[112:115], v[32:47]
	s_waitcnt lgkmcnt(3)
	v_mfma_f32_32x32x16_bf16 v[48:63], v[64:67], v[116:119], v[48:63]
	s_waitcnt lgkmcnt(1)
	v_mfma_f32_32x32x16_bf16 v[32:47], v[72:75], v[116:119], v[32:47]
	v_mfma_f32_32x32x16_bf16 v[48:63], v[68:71], v[120:123], v[48:63]
	s_waitcnt lgkmcnt(0)
	v_mfma_f32_32x32x16_bf16 v[32:47], v[76:79], v[120:123], v[32:47]
	s_cbranch_scc1 .LBB0_1114
	ds_read_b128 v[172:175], v209 offset:13312
	ds_read_b128 v[152:155], v209 offset:13344
	ds_read_b128 v[180:183], v209 offset:19968
	ds_read_b128 v[164:167], v209 offset:20000
	ds_read_b128 v[156:159], v209 offset:13376
	ds_read_b128 v[140:143], v209 offset:13408
	ds_read_b128 v[176:179], v209 offset:20032
	ds_read_b128 v[160:163], v209 offset:20064
	ds_read_b128 v[148:151], v209 offset:13440
	ds_read_b128 v[136:139], v209 offset:13472
	ds_read_b128 v[168:171], v209 offset:20096
	ds_read_b128 v[144:147], v209 offset:20128
	v_lshl_add_u64 v[0:1], s[60:61], 0, v[192:193]
	v_mov_b32_e32 v191, v97
	v_mov_b32_e32 v198, 0
	v_lshl_add_u64 v[98:99], s[96:97], 0, v[186:187]
	v_lshl_add_u64 v[202:203], s[96:97], 0, v[188:189]
	v_lshl_add_u64 v[204:205], v[0:1], 0, v[190:191]
	s_add_u32 s98, s94, 0x12209000
	s_addc_u32 s99, s95, 0
	s_add_u32 s100, s94, 0x11200000
	s_addc_u32 s101, s95, 0

	v_mov_b32_e32 v0, 0
	v_mov_b32_e32 v1, v198
	v_mov_b32_e32 v2, v198
	v_mov_b32_e32 v3, v198
	v_mov_b32_e32 v4, v198
	v_mov_b32_e32 v5, v198
	v_mov_b32_e32 v6, v198
	v_mov_b32_e32 v7, v198
	v_mov_b32_e32 v8, v198
	v_mov_b32_e32 v9, v198
	v_mov_b32_e32 v10, v198
	v_mov_b32_e32 v11, v198
	v_mov_b32_e32 v12, v198
	v_mov_b32_e32 v13, v198
	v_mov_b32_e32 v14, v198
	v_mov_b32_e32 v15, v198
	v_mov_b32_e32 v16, 0
	v_mov_b32_e32 v17, v198
	v_mov_b32_e32 v18, v198
	v_mov_b32_e32 v19, v198
	v_mov_b32_e32 v20, v198
	v_mov_b32_e32 v21, v198
	v_mov_b32_e32 v22, v198
	v_mov_b32_e32 v23, v198
	v_mov_b32_e32 v24, v198
	v_mov_b32_e32 v25, v198
	v_mov_b32_e32 v26, v198
	v_mov_b32_e32 v27, v198
	v_mov_b32_e32 v28, v198
	v_mov_b32_e32 v29, v198
	v_mov_b32_e32 v30, v198
	v_mov_b32_e32 v31, v198
	s_mov_b32 s41, 0x2c000
	s_branch .LBB0_1106
.LBB0_1106:
	s_waitcnt lgkmcnt(11)
	v_mfma_f32_32x32x16_bf16 v[64:79], v[172:175], v[100:103], 0
	v_exp_f32_e32 v48, v48
	v_exp_f32_e32 v49, v49
	v_exp_f32_e32 v50, v50
	v_add_f32_e32 v195, v48, v49
	v_exp_f32_e32 v51, v51
	s_waitcnt lgkmcnt(9)
	v_mfma_f32_32x32x16_bf16 v[80:95], v[180:183], v[100:103], 0
	v_add_f32_e32 v195, v50, v195
	v_exp_f32_e32 v52, v52
	v_add_f32_e32 v195, v51, v195
	v_exp_f32_e32 v53, v53
	v_add_f32_e32 v195, v52, v195
	v_exp_f32_e32 v54, v54
	v_add_f32_e32 v195, v53, v195
	v_mfma_f32_32x32x16_bf16 v[64:79], v[152:155], v[104:107], v[64:79]
	v_exp_f32_e32 v55, v55
	v_add_f32_e32 v195, v54, v195
	v_exp_f32_e32 v56, v56
	v_add_f32_e32 v195, v55, v195
	v_exp_f32_e32 v57, v57
	v_add_f32_e32 v195, v56, v195
	s_waitcnt lgkmcnt(8)
	v_mfma_f32_32x32x16_bf16 v[80:95], v[164:167], v[104:107], v[80:95]
	v_exp_f32_e32 v58, v58
	v_add_f32_e32 v195, v57, v195
	v_exp_f32_e32 v59, v59
	v_add_f32_e32 v195, v58, v195
	v_exp_f32_e32 v60, v60
	v_add_f32_e32 v195, v59, v195
	s_waitcnt lgkmcnt(7)
	v_mfma_f32_32x32x16_bf16 v[64:79], v[156:159], v[108:111], v[64:79]
	v_exp_f32_e32 v61, v61
	v_add_f32_e32 v195, v60, v195
	v_exp_f32_e32 v62, v62
	v_add_f32_e32 v195, v61, v195
	v_exp_f32_e32 v63, v63
	v_add_f32_e32 v195, v62, v195
	v_add_f32_e32 v195, v63, v195
	s_mul_i32 s6, s90, 0x3400
	s_add_i32 s7, s6, 0

	v_add_u32_e32 v253, s7, v96
	s_waitcnt vmcnt(1)
	ds_write_b128 v253, v[128:131]
	s_and_saveexec_b64 s[4:5], s[2:3]
	v_add_u32_e32 v253, s7, v185
	ds_write_b128 v253, v[124:127]
	s_or_b64 exec, exec, s[4:5]
	v_lshl_add_u64 v[200:201], s[100:101], 0, v[204:205]

	v_add_u32_e32 v254, 0xc000, v210
	v_lshl_add_u64 v[128:129], s[98:99], 0, v[98:99]
	s_nop 0
	global_load_dwordx4 v[128:131], v[128:129], off
	s_waitcnt vmcnt(1)
	ds_write2_b64 v254, v[132:133], v[134:135] offset1:2

	s_and_saveexec_b64 s[4:5], s[2:3]
	s_cbranch_execz .LatB_h0
	v_lshl_add_u64 v[124:125], s[98:99], 0, v[202:203]
	s_nop 0
	global_load_dwordx4 v[124:127], v[124:125], off
.LatB_h0:
	s_or_b64 exec, exec, s[4:5]
	global_load_dwordx4 v[132:135], v[200:201], off offset:256

	s_waitcnt lgkmcnt(7)
	v_mfma_f32_32x32x16_bf16 v[80:95], v[176:179], v[108:111], v[80:95]
	v_exp_f32_e32 v32, v32
	v_exp_f32_e32 v33, v33
	v_exp_f32_e32 v34, v34
	v_add_f32_e32 v251, v32, v33
	v_cvt_pk_bf16_f32 v48, v48, v49
	v_exp_f32_e32 v35, v35
	v_mfma_f32_32x32x16_bf16 v[64:79], v[140:143], v[112:115], v[64:79]
	v_add_f32_e32 v251, v34, v251
	v_exp_f32_e32 v36, v36
	v_add_f32_e32 v251, v35, v251
	v_cvt_pk_bf16_f32 v49, v50, v51
	v_exp_f32_e32 v37, v37
	v_add_f32_e32 v251, v36, v251
	s_waitcnt lgkmcnt(6)
	v_mfma_f32_32x32x16_bf16 v[80:95], v[160:163], v[112:115], v[80:95]
	v_exp_f32_e32 v38, v38
	v_add_f32_e32 v251, v37, v251
	v_cvt_pk_bf16_f32 v50, v52, v53
	v_exp_f32_e32 v39, v39
	v_add_f32_e32 v251, v38, v251
	v_exp_f32_e32 v40, v40
	v_add_f32_e32 v251, v39, v251
	s_waitcnt lgkmcnt(5)
	v_mfma_f32_32x32x16_bf16 v[64:79], v[148:151], v[116:119], v[64:79]
	v_cvt_pk_bf16_f32 v51, v54, v55
	v_exp_f32_e32 v41, v41
	v_add_f32_e32 v251, v40, v251
	v_exp_f32_e32 v42, v42
	v_add_f32_e32 v251, v41, v251
	v_cvt_pk_bf16_f32 v52, v56, v57
	v_exp_f32_e32 v43, v43
	v_add_u32_e32 v196, v208, v184
	ds_read_b128 v[212:215], v196 offset:44544
	ds_read_b128 v[216:219], v196 offset:39936
	ds_read_b128 v[220:223], v196 offset:39968
	ds_read_b128 v[224:227], v196 offset:44576
	ds_read_b128 v[228:231], v196 offset:40000
	ds_read_b128 v[232:235], v196 offset:44608
	ds_read_b128 v[236:239], v196 offset:40032
	ds_read_b128 v[240:243], v196 offset:44640
	s_waitcnt lgkmcnt(11)
	v_mfma_f32_32x32x16_bf16 v[80:95], v[168:171], v[116:119], v[80:95]
	v_add_f32_e32 v251, v42, v251
	v_exp_f32_e32 v44, v44
	v_add_f32_e32 v251, v43, v251
	v_cvt_pk_bf16_f32 v53, v58, v59
	v_exp_f32_e32 v45, v45
	v_add_f32_e32 v251, v44, v251
	v_mfma_f32_32x32x16_bf16 v[64:79], v[136:139], v[120:123], v[64:79]
	v_exp_f32_e32 v46, v46
	v_add_f32_e32 v251, v45, v251
	v_cvt_pk_bf16_f32 v54, v60, v61
	v_exp_f32_e32 v47, v47
	v_add_f32_e32 v251, v46, v251
	v_add_f32_e32 v251, v47, v251
	v_cvt_pk_bf16_f32 v55, v62, v63
	v_cvt_pk_bf16_f32 v32, v32, v33
	s_waitcnt lgkmcnt(10)
	v_mfma_f32_32x32x16_bf16 v[80:95], v[144:147], v[120:123], v[80:95]
	v_cvt_pk_bf16_f32 v33, v34, v35
	v_cvt_pk_bf16_f32 v34, v36, v37
	v_cvt_pk_bf16_f32 v35, v38, v39
	v_cvt_pk_bf16_f32 v36, v40, v41
	v_cvt_pk_bf16_f32 v37, v42, v43
	v_cvt_pk_bf16_f32 v38, v44, v45
	v_cvt_pk_bf16_f32 v39, v46, v47
	v_add_f32_e32 v195, v195, v251
	v_add_f32_e32 v198, v198, v195
	s_waitcnt lgkmcnt(0)
	s_barrier

	v_add_u32_e32 v197, s6, v209
	s_setprio 1
	v_mfma_f32_32x32x16_bf16 v[0:15], v[48:51], v[212:215], v[0:15]
	ds_read_b128 v[172:175], v197
	ds_read_b128 v[152:155], v197 offset:32
	v_mfma_f32_32x32x16_bf16 v[0:15], v[52:55], v[224:227], v[0:15]
	ds_read_b128 v[180:183], v197 offset:6656
	ds_read_b128 v[164:167], v197 offset:6688
	v_mfma_f32_32x32x16_bf16 v[0:15], v[32:35], v[232:235], v[0:15]
	ds_read_b128 v[156:159], v197 offset:64
	ds_read_b128 v[140:143], v197 offset:96
	v_mfma_f32_32x32x16_bf16 v[0:15], v[36:39], v[240:243], v[0:15]
	s_setprio 0
	ds_read_b128 v[176:179], v197 offset:6720
	ds_read_b128 v[160:163], v197 offset:6752
	v_mfma_f32_32x32x16_bf16 v[16:31], v[48:51], v[216:219], v[16:31]
	ds_read_b128 v[148:151], v197 offset:128
	ds_read_b128 v[136:139], v197 offset:160
	v_mfma_f32_32x32x16_bf16 v[16:31], v[52:55], v[220:223], v[16:31]
	ds_read_b128 v[168:171], v197 offset:6784
	ds_read_b128 v[144:147], v197 offset:6816
	v_mfma_f32_32x32x16_bf16 v[16:31], v[32:35], v[228:231], v[16:31]
	v_mfma_f32_32x32x16_bf16 v[16:31], v[36:39], v[236:239], v[16:31]
	s_waitcnt lgkmcnt(11)
	v_mfma_f32_32x32x16_bf16 v[48:63], v[172:175], v[100:103], 0
	v_exp_f32_e32 v64, v64
	v_exp_f32_e32 v65, v65
	v_exp_f32_e32 v66, v66
	v_add_f32_e32 v195, v64, v65
	v_exp_f32_e32 v67, v67
	s_waitcnt lgkmcnt(9)
	v_mfma_f32_32x32x16_bf16 v[32:47], v[180:183], v[100:103], 0
	v_add_f32_e32 v195, v66, v195
	v_exp_f32_e32 v68, v68
	v_add_f32_e32 v195, v67, v195
	v_exp_f32_e32 v69, v69
	v_add_f32_e32 v195, v68, v195
	v_exp_f32_e32 v70, v70
	v_add_f32_e32 v195, v69, v195
	v_mfma_f32_32x32x16_bf16 v[48:63], v[152:155], v[104:107], v[48:63]
	v_exp_f32_e32 v71, v71
	v_add_f32_e32 v195, v70, v195
	v_exp_f32_e32 v72, v72
	v_add_f32_e32 v195, v71, v195
	v_exp_f32_e32 v73, v73
	v_add_f32_e32 v195, v72, v195
	s_waitcnt lgkmcnt(8)
	v_mfma_f32_32x32x16_bf16 v[32:47], v[164:167], v[104:107], v[32:47]
	v_exp_f32_e32 v74, v74
	v_add_f32_e32 v195, v73, v195
	v_exp_f32_e32 v75, v75
	v_add_f32_e32 v195, v74, v195
	v_exp_f32_e32 v76, v76
	v_add_f32_e32 v195, v75, v195
	s_waitcnt lgkmcnt(7)
	v_mfma_f32_32x32x16_bf16 v[48:63], v[156:159], v[108:111], v[48:63]
	v_exp_f32_e32 v77, v77
	v_add_f32_e32 v195, v76, v195
	v_exp_f32_e32 v78, v78
	v_add_f32_e32 v195, v77, v195
	v_exp_f32_e32 v79, v79
	v_add_f32_e32 v195, v78, v195
	v_add_f32_e32 v195, v79, v195
	s_add_i32 s4, s90, 1
	s_cmp_lg_u32 s90, 2
	s_cselect_b32 s68, s4, 0
	s_mul_i32 s6, s68, 0x3400
	s_add_i32 s7, s6, 0
	s_add_u32 s98, s98, 0x3000
	s_addc_u32 s99, s99, 0

	v_add_u32_e32 v253, s7, v96
	s_waitcnt vmcnt(1)
	ds_write_b128 v253, v[128:131]
	s_and_saveexec_b64 s[4:5], s[2:3]
	v_add_u32_e32 v253, s7, v185
	ds_write_b128 v253, v[124:127]
	s_or_b64 exec, exec, s[4:5]
	v_lshl_add_u64 v[200:201], s[100:101], 0, v[204:205]

	s_waitcnt vmcnt(0)
	ds_write2_b64 v211, v[132:133], v[134:135] offset0:128 offset1:130
	v_lshl_add_u64 v[128:129], s[98:99], 0, v[98:99]
	s_nop 0
	global_load_dwordx4 v[128:131], v[128:129], off

	s_and_saveexec_b64 s[4:5], s[2:3]
	s_cbranch_execz .LatB_h1
	v_lshl_add_u64 v[124:125], s[98:99], 0, v[202:203]
	s_nop 0
	global_load_dwordx4 v[124:127], v[124:125], off
.LatB_h1:
	s_or_b64 exec, exec, s[4:5]
	global_load_dwordx4 v[132:135], v[200:201], off offset:384

	s_sub_u32 s98, s98, 0x3000
	s_subb_u32 s99, s99, 0

	s_waitcnt lgkmcnt(7)
	v_mfma_f32_32x32x16_bf16 v[32:47], v[176:179], v[108:111], v[32:47]
	v_exp_f32_e32 v80, v80
	v_exp_f32_e32 v81, v81
	v_exp_f32_e32 v82, v82
	v_add_f32_e32 v251, v80, v81
	v_cvt_pk_bf16_f32 v64, v64, v65
	v_exp_f32_e32 v83, v83
	v_mfma_f32_32x32x16_bf16 v[48:63], v[140:143], v[112:115], v[48:63]
	v_add_f32_e32 v251, v82, v251
	v_exp_f32_e32 v84, v84
	v_add_f32_e32 v251, v83, v251
	v_cvt_pk_bf16_f32 v65, v66, v67
	v_exp_f32_e32 v85, v85
	v_add_f32_e32 v251, v84, v251
	s_waitcnt lgkmcnt(6)
	v_mfma_f32_32x32x16_bf16 v[32:47], v[160:163], v[112:115], v[32:47]
	v_exp_f32_e32 v86, v86
	v_add_f32_e32 v251, v85, v251
	v_cvt_pk_bf16_f32 v66, v68, v69
	v_exp_f32_e32 v87, v87
	v_add_f32_e32 v251, v86, v251
	v_exp_f32_e32 v88, v88
	v_add_f32_e32 v251, v87, v251
	s_waitcnt lgkmcnt(5)
	v_mfma_f32_32x32x16_bf16 v[48:63], v[148:151], v[116:119], v[48:63]
	v_cvt_pk_bf16_f32 v67, v70, v71
	v_exp_f32_e32 v89, v89
	v_add_f32_e32 v251, v88, v251
	v_exp_f32_e32 v90, v90
	v_add_f32_e32 v251, v89, v251
	v_cvt_pk_bf16_f32 v68, v72, v73
	v_exp_f32_e32 v91, v91
	v_add_u32_e32 v196, v208, v184
	ds_read_b128 v[212:215], v196 offset:53760
	ds_read_b128 v[216:219], v196 offset:49152
	ds_read_b128 v[220:223], v196 offset:49184
	ds_read_b128 v[224:227], v196 offset:53792
	ds_read_b128 v[228:231], v196 offset:49216
	ds_read_b128 v[232:235], v196 offset:53824
	ds_read_b128 v[236:239], v196 offset:49248
	ds_read_b128 v[240:243], v196 offset:53856
	s_waitcnt lgkmcnt(11)
	v_mfma_f32_32x32x16_bf16 v[32:47], v[168:171], v[116:119], v[32:47]
	v_add_f32_e32 v251, v90, v251
	v_exp_f32_e32 v92, v92
	v_add_f32_e32 v251, v91, v251
	v_cvt_pk_bf16_f32 v69, v74, v75
	v_exp_f32_e32 v93, v93
	v_add_f32_e32 v251, v92, v251
	v_mfma_f32_32x32x16_bf16 v[48:63], v[136:139], v[120:123], v[48:63]
	v_exp_f32_e32 v94, v94
	v_add_f32_e32 v251, v93, v251
	v_cvt_pk_bf16_f32 v70, v76, v77
	v_exp_f32_e32 v95, v95
	v_add_f32_e32 v251, v94, v251
	v_add_f32_e32 v251, v95, v251
	v_cvt_pk_bf16_f32 v71, v78, v79
	v_cvt_pk_bf16_f32 v80, v80, v81
	s_waitcnt lgkmcnt(10)
	v_mfma_f32_32x32x16_bf16 v[32:47], v[144:147], v[120:123], v[32:47]
	v_cvt_pk_bf16_f32 v81, v82, v83
	v_cvt_pk_bf16_f32 v82, v84, v85
	v_cvt_pk_bf16_f32 v83, v86, v87
	v_cvt_pk_bf16_f32 v84, v88, v89
	v_cvt_pk_bf16_f32 v85, v90, v91
	v_cvt_pk_bf16_f32 v86, v92, v93
	v_cvt_pk_bf16_f32 v87, v94, v95
	v_add_f32_e32 v195, v195, v251
	v_add_f32_e32 v198, v198, v195
	s_add_i32 s40, s40, 2
	s_waitcnt lgkmcnt(0)
	s_barrier

	v_add_u32_e32 v197, s6, v209
	s_setprio 1
	v_mfma_f32_32x32x16_bf16 v[0:15], v[64:67], v[212:215], v[0:15]
	ds_read_b128 v[172:175], v197
	ds_read_b128 v[152:155], v197 offset:32
	v_mfma_f32_32x32x16_bf16 v[0:15], v[68:71], v[224:227], v[0:15]
	ds_read_b128 v[180:183], v197 offset:6656
	ds_read_b128 v[164:167], v197 offset:6688
	v_mfma_f32_32x32x16_bf16 v[0:15], v[80:83], v[232:235], v[0:15]
	ds_read_b128 v[156:159], v197 offset:64
	ds_read_b128 v[140:143], v197 offset:96
	v_mfma_f32_32x32x16_bf16 v[0:15], v[84:87], v[240:243], v[0:15]
	s_setprio 0
	ds_read_b128 v[176:179], v197 offset:6720
	ds_read_b128 v[160:163], v197 offset:6752
	v_mfma_f32_32x32x16_bf16 v[16:31], v[64:67], v[216:219], v[16:31]
	ds_read_b128 v[148:151], v197 offset:128
	ds_read_b128 v[136:139], v197 offset:160
	v_mfma_f32_32x32x16_bf16 v[16:31], v[68:71], v[220:223], v[16:31]
	ds_read_b128 v[168:171], v197 offset:6784
	ds_read_b128 v[144:147], v197 offset:6816
	v_mfma_f32_32x32x16_bf16 v[16:31], v[80:83], v[228:231], v[16:31]
	v_mfma_f32_32x32x16_bf16 v[16:31], v[84:87], v[236:239], v[16:31]
	s_add_i32 s4, s68, 1
	s_cmp_lg_u32 s68, 2
	s_cselect_b32 s90, s4, 0
	v_lshl_add_u64 v[98:99], v[98:99], 0, s[82:83]
	v_lshl_add_u64 v[202:203], v[202:203], 0, s[82:83]
	s_cmp_ge_u32 s40, s69
	v_lshl_add_u64 v[204:205], v[204:205], 0, s[66:67]
	s_cbranch_scc1 .LBB0_1115
	s_branch .LBB0_1106

